# static s_setprio 1 for waves 0-3 (older half) instead of 4-7, per-block flips removed
# speedup vs baseline: 1.0123x; 1.0031x over previous
;     __device__ bool next(int i, Unit& u) const { const int idx = i * G + c; if (idx >= 64) return false; u.kp = idx & 3; u.pn = (idx >> 2) & 7; u.pm = 192 + (idx >> 5); return true; }
; #define PG8_STAGE(bufoff, gbase, voff) do { _Pragma("unroll") for (int _i = 0; _i < 2; ++_i) \
;         __builtin_amdgcn_global_load_lds((const unsigned*)((const char*)(gbase) + (voff)[_i]), (LAS unsigned*)(lds + (bufoff) + ldsw + _i * 8192), 16, 0, 0); } while (0)
; #define PG8_WAIT_V(n) asm volatile("s_waitcnt vmcnt(" #n ")" ::: "memory")
; #define PG8_BAR __builtin_amdgcn_s_barrier()
; template <class Epi, class Sched = StaticOrder, bool ALIGN_EPI = true>
; __device__ __forceinline__ void gemm_phase(LAS unsigned char* lds, const Gemm g, const Sched& S, const Epi& E) {
;     ...
;     for (int i = 0; i < 2; ++i) { int R, C; stage_rc(tid * 16 + i * 8192, R, C); const int Rb = Epi::PERM ? ((R & ~31) + perm32(R & 31)) : R;
;         voffA[i] = (unsigned)(R * g.ld + C) * 2u; voffB[i] = (unsigned)(Rb * g.ld + C) * 2u; }
;     const size_t kstep = (size_t)(BK * 2);
;     const size_t hstep = (size_t)HALF * g.ld * 2;
;     const size_t tstep = 2 * hstep;
;     const unsigned ldsw = (unsigned)wid * 1024u;
;     const int aoff = lds_byte(wr * 64 + fr, fq * 8), boff = lds_byte(wc * 32 + fr, fq * 8);
;     ...
;     Unit cur, nxt; int ui = 0;
;     if (!S.next(0, cur)) return;
;     f32x4 acc[2][2][4][2];
; #pragma unroll
;     for (int a = 0; a < 2; ++a)
; #pragma unroll
;         for (int b = 0; b < 2; ++b)
; #pragma unroll
;             for (int m = 0; m < 4; ++m)
; #pragma unroll
;                 for (int n = 0; n < 2; ++n) acc[a][b][m][n] = (f32x4){0.f, 0.f, 0.f, 0.f};
;     bf16x8 At[4][2], B0[2][2], B1[2][2];
;     const char* cA = (const char*)g.A + (size_t)cur.pm * tstep + (size_t)cur.kp * K * 2; const char* cB = (const char*)g.Bt + (size_t)cur.pn * tstep + (size_t)cur.kp * K * 2;
;     PG8_STAGE(PG8_SB(0, 0), cB, voffB); PG8_STAGE(PG8_SB(0, 1), cB + hstep, voffB); PG8_STAGE(PG8_SA(0, 0), cA, voffA); PG8_STAGE(PG8_SA(0, 1), cA + hstep, voffA);
;     if (wr == 1) PG8_BAR;
;     PG8_WAIT_V(2); PG8_BAR;
;     PG8_STAGE(PG8_SB(1, 0), cB + kstep, voffB); PG8_STAGE(PG8_SA(1, 0), cA + kstep, voffA); PG8_STAGE(PG8_SB(1, 1), cB + hstep + kstep, voffB);
;     PG8_WAIT_V(6); PG8_BAR;
.LBB0_100:
	v_lshrrev_b32_e32 v18, 1, v16
	v_and_b32_e32 v18, 24, v18
	v_and_b32_e32 v17, 15, v16
	v_lshlrev_b32_e32 v19, 1, v18
	v_lshlrev_b32_e32 v16, 2, v16
	s_sext_i32_i8 s23, s0
	v_lshl_or_b32 v1, s12, 6, v17
	v_lshl_or_b32 v17, v17, 6, v19
	s_lshl_b32 s0, s12, 13
	v_and_b32_e32 v16, 32, v16
	v_bitop3_b32 v19, v17, s0, v16 bitop3:0xde
	s_lshl_b32 s0, s11, 5
	s_and_b32 s0, s0, 0x60
	s_lshl_b32 s11, s0, 7
	s_add_i32 m0, s7, 0x18000
	v_lshl_add_u64 v[8:9], v[8:9], 0, s[34:35]
	v_bitop3_b32 v144, v17, s11, v16 bitop3:0xde
	s_waitcnt vmcnt(2)
	s_barrier
	global_load_lds_dwordx4 v[8:9], off
	v_lshl_add_u64 v[6:7], v[6:7], 0, s[34:35]
	s_add_i32 m0, s7, 0x1a000
	s_add_i32 s11, s7, 0x8000
	s_add_i32 s18, s7, 0xa000
	global_load_lds_dwordx4 v[6:7], off
	v_lshl_add_u64 v[2:3], v[2:3], 0, s[34:35]
	s_mov_b32 m0, s11
	s_add_u32 s12, s46, 0x80080
	global_load_lds_dwordx4 v[2:3], off
	v_lshl_add_u64 v[2:3], v[4:5], 0, s[34:35]
	s_mov_b32 m0, s18
	s_addc_u32 s13, s47, 0
	global_load_lds_dwordx4 v[2:3], off
	s_add_i32 m0, s7, 0x1c000
	v_lshl_add_u64 v[2:3], s[12:13], 0, v[134:135]
	global_load_lds_dwordx4 v[2:3], off
	v_lshl_add_u64 v[2:3], s[12:13], 0, v[130:131]
	s_add_i32 m0, s7, 0x1e000
	s_cmpk_lt_u32 s1, 0x100
	global_load_lds_dwordx4 v[2:3], off
	v_lshlrev_b32_e32 v2, 15, v14
	v_and_b32_e32 v2, 0xffff0000, v2
	v_lshl_add_u32 v2, v13, 12, v2
	v_and_b32_e32 v3, 1, v14
	v_lshl_or_b32 v2, v3, 6, v2
	v_lshl_add_u32 v138, v15, 1, v2
	v_lshlrev_b32_e32 v2, 15, v10
	v_and_b32_e32 v2, 0xffff0000, v2
	s_waitcnt vmcnt(6)
	v_lshl_add_u32 v2, v11, 12, v2
	v_and_b32_e32 v3, 1, v10
	v_lshl_or_b32 v2, v3, 6, v2
	s_cselect_b64 s[12:13], -1, 0
	v_or_b32_e32 v145, s0, v18
	v_mov_b32_e32 v139, v0
	v_lshl_add_u32 v140, v12, 1, v2
	v_mov_b32_e32 v141, v0
	s_mov_b32 s22, 0
	v_add_u32_e32 v146, 0, v19
	s_barrier
	s_cmp_eq_u64 s[12:13], 0
	s_cbranch_scc1 .Lmy_pr_103
	s_setprio 1

;     __device__ bool next(int i, Unit& u) const { const int idx = i * G + c; if (idx >= 64) return false; u.kp = idx & 3; u.pn = (idx >> 2) & 7; u.pm = 192 + (idx >> 5); return true; }
; #define PG8_STAGE(bufoff, gbase, voff) do { _Pragma("unroll") for (int _i = 0; _i < 2; ++_i) \
;         __builtin_amdgcn_global_load_lds((const unsigned*)((const char*)(gbase) + (voff)[_i]), (LAS unsigned*)(lds + (bufoff) + ldsw + _i * 8192), 16, 0, 0); } while (0)
; #define PG8_WAIT_V(n) asm volatile("s_waitcnt vmcnt(" #n ")" ::: "memory")
; #define PG8_BAR __builtin_amdgcn_s_barrier()
; template <class Epi, class Sched = StaticOrder, bool ALIGN_EPI = true>
; __device__ __forceinline__ void gemm_phase(LAS unsigned char* lds, const Gemm g, const Sched& S, const Epi& E) {
;     ...
;     for (int i = 0; i < 2; ++i) { int R, C; stage_rc(tid * 16 + i * 8192, R, C); const int Rb = Epi::PERM ? ((R & ~31) + perm32(R & 31)) : R;
;         voffA[i] = (unsigned)(R * g.ld + C) * 2u; voffB[i] = (unsigned)(Rb * g.ld + C) * 2u; }
;     const size_t kstep = (size_t)(BK * 2);
;     const size_t hstep = (size_t)HALF * g.ld * 2;
;     const size_t tstep = 2 * hstep;
;     const unsigned ldsw = (unsigned)wid * 1024u;
;     const int aoff = lds_byte(wr * 64 + fr, fq * 8), boff = lds_byte(wc * 32 + fr, fq * 8);
;     ...
;     Unit cur, nxt; int ui = 0;
;     if (!S.next(0, cur)) return;
;     f32x4 acc[2][2][4][2];
; #pragma unroll
;     for (int a = 0; a < 2; ++a)
; #pragma unroll
;         for (int b = 0; b < 2; ++b)
; #pragma unroll
;             for (int m = 0; m < 4; ++m)
; #pragma unroll
;                 for (int n = 0; n < 2; ++n) acc[a][b][m][n] = (f32x4){0.f, 0.f, 0.f, 0.f};
;     bf16x8 At[4][2], B0[2][2], B1[2][2];
;     const char* cA = (const char*)g.A + (size_t)cur.pm * tstep + (size_t)cur.kp * K * 2; const char* cB = (const char*)g.Bt + (size_t)cur.pn * tstep + (size_t)cur.kp * K * 2;
;     PG8_STAGE(PG8_SB(0, 0), cB, voffB); PG8_STAGE(PG8_SB(0, 1), cB + hstep, voffB); PG8_STAGE(PG8_SA(0, 0), cA, voffA); PG8_STAGE(PG8_SA(0, 1), cA + hstep, voffA);
;     if (wr == 1) PG8_BAR;
;     PG8_WAIT_V(2); PG8_BAR;
;     PG8_STAGE(PG8_SB(1, 0), cB + kstep, voffB); PG8_STAGE(PG8_SA(1, 0), cA + kstep, voffA); PG8_STAGE(PG8_SB(1, 1), cB + hstep + kstep, voffB);
;     PG8_WAIT_V(6); PG8_BAR;
.LBB0_330:
	v_lshrrev_b32_e32 v18, 1, v16
	v_and_b32_e32 v18, 24, v18
	s_lshl_b32 s11, s11, 5
	v_and_b32_e32 v17, 15, v16
	v_lshlrev_b32_e32 v19, 1, v18
	v_lshlrev_b32_e32 v16, 2, v16
	s_and_b32 s20, s11, 0x60
	v_lshl_or_b32 v1, s18, 6, v17
	v_lshl_or_b32 v17, v17, 6, v19
	v_and_b32_e32 v16, 32, v16
	s_lshl_b32 s11, s20, 7
	s_add_i32 m0, s7, 0x18000
	v_lshl_add_u64 v[8:9], v[8:9], 0, s[34:35]
	s_sext_i32_i8 s23, s12
	s_lshl_b32 s12, s18, 13
	v_bitop3_b32 v144, v17, s11, v16 bitop3:0xde
	s_waitcnt vmcnt(2)
	s_barrier
	global_load_lds_dwordx4 v[8:9], off
	v_lshl_add_u64 v[6:7], v[6:7], 0, s[34:35]
	s_add_i32 m0, s7, 0x1a000
	s_add_i32 s11, s7, 0x8000
	s_add_i32 s18, s7, 0xa000
	global_load_lds_dwordx4 v[6:7], off
	v_lshl_add_u64 v[2:3], v[2:3], 0, s[34:35]
	s_mov_b32 m0, s11
	s_add_u32 s16, s92, 0x80080
	global_load_lds_dwordx4 v[2:3], off
	v_lshl_add_u64 v[2:3], v[4:5], 0, s[34:35]
	s_mov_b32 m0, s18
	s_addc_u32 s17, s93, 0
	global_load_lds_dwordx4 v[2:3], off
	s_add_i32 m0, s7, 0x1c000
	v_lshl_add_u64 v[2:3], s[16:17], 0, v[134:135]
	global_load_lds_dwordx4 v[2:3], off
	v_lshl_add_u64 v[2:3], s[16:17], 0, v[130:131]
	s_add_i32 m0, s7, 0x1e000
	v_bitop3_b32 v19, v17, s12, v16 bitop3:0xde
	global_load_lds_dwordx4 v[2:3], off
	v_lshlrev_b32_e32 v2, 15, v14
	v_and_b32_e32 v2, 0xffff0000, v2
	v_lshl_add_u32 v2, v13, 12, v2
	v_and_b32_e32 v3, 1, v14
	v_lshl_or_b32 v2, v3, 6, v2
	v_lshl_add_u32 v138, v15, 1, v2
	v_lshlrev_b32_e32 v2, 15, v10
	v_and_b32_e32 v2, 0xffff0000, v2
	s_waitcnt vmcnt(6)
	v_lshl_add_u32 v2, v11, 12, v2
	v_and_b32_e32 v3, 1, v10
	s_cmpk_lt_u32 s13, 0x100
	v_lshl_or_b32 v2, v3, 6, v2
	s_cselect_b64 s[12:13], -1, 0
	v_or_b32_e32 v145, s20, v18
	v_mov_b32_e32 v139, v0
	v_lshl_add_u32 v140, v12, 1, v2
	v_mov_b32_e32 v141, v0
	s_mov_b32 s22, 0
	v_add_u32_e32 v146, 0, v19
	s_barrier
	s_waitcnt vmcnt(0)
	s_cmp_eq_u64 s[12:13], 0
	s_cbranch_scc1 .Lmy_pr_333
	s_setprio 1

;     __device__ bool next(int i, Unit& u) const { const int idx = i * G + c; if (idx >= 64) return false; u.kp = idx & 3; u.pn = (idx >> 2) & 7; u.pm = 192 + (idx >> 5); return true; }
; #define PG8_STAGE(bufoff, gbase, voff) do { _Pragma("unroll") for (int _i = 0; _i < 2; ++_i) \
;         __builtin_amdgcn_global_load_lds((const unsigned*)((const char*)(gbase) + (voff)[_i]), (LAS unsigned*)(lds + (bufoff) + ldsw + _i * 8192), 16, 0, 0); } while (0)
; #define PG8_WAIT_V(n) asm volatile("s_waitcnt vmcnt(" #n ")" ::: "memory")
; #define PG8_BAR __builtin_amdgcn_s_barrier()
; template <class Epi, class Sched = StaticOrder, bool ALIGN_EPI = true>
; __device__ __forceinline__ void gemm_phase(LAS unsigned char* lds, const Gemm g, const Sched& S, const Epi& E) {
;     ...
;     for (int i = 0; i < 2; ++i) { int R, C; stage_rc(tid * 16 + i * 8192, R, C); const int Rb = Epi::PERM ? ((R & ~31) + perm32(R & 31)) : R;
;         voffA[i] = (unsigned)(R * g.ld + C) * 2u; voffB[i] = (unsigned)(Rb * g.ld + C) * 2u; }
;     const size_t kstep = (size_t)(BK * 2);
;     const size_t hstep = (size_t)HALF * g.ld * 2;
;     const size_t tstep = 2 * hstep;
;     const unsigned ldsw = (unsigned)wid * 1024u;
;     const int aoff = lds_byte(wr * 64 + fr, fq * 8), boff = lds_byte(wc * 32 + fr, fq * 8);
;     ...
;     Unit cur, nxt; int ui = 0;
;     if (!S.next(0, cur)) return;
;     f32x4 acc[2][2][4][2];
; #pragma unroll
;     for (int a = 0; a < 2; ++a)
; #pragma unroll
;         for (int b = 0; b < 2; ++b)
; #pragma unroll
;             for (int m = 0; m < 4; ++m)
; #pragma unroll
;                 for (int n = 0; n < 2; ++n) acc[a][b][m][n] = (f32x4){0.f, 0.f, 0.f, 0.f};
;     bf16x8 At[4][2], B0[2][2], B1[2][2];
;     const char* cA = (const char*)g.A + (size_t)cur.pm * tstep + (size_t)cur.kp * K * 2; const char* cB = (const char*)g.Bt + (size_t)cur.pn * tstep + (size_t)cur.kp * K * 2;
;     PG8_STAGE(PG8_SB(0, 0), cB, voffB); PG8_STAGE(PG8_SB(0, 1), cB + hstep, voffB); PG8_STAGE(PG8_SA(0, 0), cA, voffA); PG8_STAGE(PG8_SA(0, 1), cA + hstep, voffA);
;     if (wr == 1) PG8_BAR;
;     PG8_WAIT_V(2); PG8_BAR;
;     PG8_STAGE(PG8_SB(1, 0), cB + kstep, voffB); PG8_STAGE(PG8_SA(1, 0), cA + kstep, voffA); PG8_STAGE(PG8_SB(1, 1), cB + hstep + kstep, voffB);
;     PG8_WAIT_V(6); PG8_BAR;
.LBB0_360:
	v_lshrrev_b32_e32 v20, 1, v18
	v_and_b32_e32 v20, 24, v20
	v_and_b32_e32 v19, 15, v18
	v_lshlrev_b32_e32 v21, 1, v20
	v_lshlrev_b32_e32 v18, 2, v18
	s_lshl_b32 s1, s1, 5
	v_lshl_or_b32 v1, s10, 6, v19
	v_lshl_or_b32 v19, v19, 6, v21
	s_lshl_b32 s10, s10, 13
	v_and_b32_e32 v18, 32, v18
	s_and_b32 s1, s1, 0x60
	v_bitop3_b32 v21, v19, s10, v18 bitop3:0xde
	s_lshl_b32 s10, s1, 7
	s_add_i32 m0, s6, 0x18000
	v_lshl_add_u64 v[8:9], v[8:9], 0, s[34:35]
	s_sext_i32_i8 s70, s11
	v_bitop3_b32 v144, v19, s10, v18 bitop3:0xde
	s_waitcnt vmcnt(2)
	s_barrier
	global_load_lds_dwordx4 v[8:9], off
	v_lshl_add_u64 v[6:7], v[6:7], 0, s[34:35]
	s_add_i32 m0, s6, 0x1a000
	s_add_i32 s10, s6, 0x8000
	s_add_i32 s11, s6, 0xa000
	global_load_lds_dwordx4 v[6:7], off
	v_lshl_add_u64 v[2:3], v[2:3], 0, s[34:35]
	s_mov_b32 m0, s10
	s_add_u32 s16, s46, 0x160080
	global_load_lds_dwordx4 v[2:3], off
	v_lshl_add_u64 v[2:3], v[4:5], 0, s[34:35]
	s_mov_b32 m0, s11
	s_addc_u32 s17, s47, 0
	global_load_lds_dwordx4 v[2:3], off
	s_add_i32 m0, s6, 0x1c000
	v_lshl_add_u64 v[2:3], s[16:17], 0, v[134:135]
	global_load_lds_dwordx4 v[2:3], off
	v_lshl_add_u64 v[2:3], s[16:17], 0, v[130:131]
	s_add_i32 m0, s6, 0x1e000
	s_movk_i32 s17, 0x1600
	global_load_lds_dwordx4 v[2:3], off
	v_lshrrev_b32_e32 v3, 1, v15
	v_mul_lo_u32 v2, v14, s17
	s_mov_b32 s16, 0x16000
	s_cmpk_lt_u32 s0, 0x100
	v_or_b32_e32 v145, s1, v20
	v_mad_u64_u32 v[2:3], s[0:1], v3, s16, v[2:3]
	v_or_b32_e32 v2, v2, v16
	v_add_lshl_u32 v2, v2, v17, 1
	v_mov_b32_e32 v3, v0
	s_mov_b64 s[22:23], 0x160080
	v_lshl_add_u64 v[138:139], v[2:3], 0, s[22:23]
	v_lshrrev_b32_e32 v3, 1, v10
	v_mul_lo_u32 v2, v11, s17
	v_mad_u64_u32 v[2:3], s[0:1], v3, s16, v[2:3]
	s_waitcnt vmcnt(6)
	v_or_b32_e32 v2, v2, v12
	v_add_lshl_u32 v2, v2, v13, 1
	v_mov_b32_e32 v3, v0
	s_cselect_b64 s[20:21], -1, 0
	v_lshl_add_u64 v[140:141], v[2:3], 0, s[22:23]
	s_mov_b32 s22, 0
	v_add_u32_e32 v146, 0, v21
	s_barrier
	s_waitcnt vmcnt(0)
	s_cmp_eq_u64 s[20:21], 0
	s_cbranch_scc1 .Lmy_pr_363
	s_setprio 1

;     __device__ bool next(int i, Unit& u) const { const int idx = i * G + c; if (idx >= 64) return false; u.kp = idx & 3; u.pn = (idx >> 2) & 7; u.pm = 192 + (idx >> 5); return true; }
; #define PG8_STAGE(bufoff, gbase, voff) do { _Pragma("unroll") for (int _i = 0; _i < 2; ++_i) \
;         __builtin_amdgcn_global_load_lds((const unsigned*)((const char*)(gbase) + (voff)[_i]), (LAS unsigned*)(lds + (bufoff) + ldsw + _i * 8192), 16, 0, 0); } while (0)
; #define PG8_WAIT_V(n) asm volatile("s_waitcnt vmcnt(" #n ")" ::: "memory")
; #define PG8_BAR __builtin_amdgcn_s_barrier()
; template <class Epi, class Sched = StaticOrder, bool ALIGN_EPI = true>
; __device__ __forceinline__ void gemm_phase(LAS unsigned char* lds, const Gemm g, const Sched& S, const Epi& E) {
;     ...
;     for (int i = 0; i < 2; ++i) { int R, C; stage_rc(tid * 16 + i * 8192, R, C); const int Rb = Epi::PERM ? ((R & ~31) + perm32(R & 31)) : R;
;         voffA[i] = (unsigned)(R * g.ld + C) * 2u; voffB[i] = (unsigned)(Rb * g.ld + C) * 2u; }
;     const size_t kstep = (size_t)(BK * 2);
;     const size_t hstep = (size_t)HALF * g.ld * 2;
;     const size_t tstep = 2 * hstep;
;     const unsigned ldsw = (unsigned)wid * 1024u;
;     const int aoff = lds_byte(wr * 64 + fr, fq * 8), boff = lds_byte(wc * 32 + fr, fq * 8);
;     ...
;     Unit cur, nxt; int ui = 0;
;     if (!S.next(0, cur)) return;
;     f32x4 acc[2][2][4][2];
; #pragma unroll
;     for (int a = 0; a < 2; ++a)
; #pragma unroll
;         for (int b = 0; b < 2; ++b)
; #pragma unroll
;             for (int m = 0; m < 4; ++m)
; #pragma unroll
;                 for (int n = 0; n < 2; ++n) acc[a][b][m][n] = (f32x4){0.f, 0.f, 0.f, 0.f};
;     bf16x8 At[4][2], B0[2][2], B1[2][2];
;     const char* cA = (const char*)g.A + (size_t)cur.pm * tstep + (size_t)cur.kp * K * 2; const char* cB = (const char*)g.Bt + (size_t)cur.pn * tstep + (size_t)cur.kp * K * 2;
;     PG8_STAGE(PG8_SB(0, 0), cB, voffB); PG8_STAGE(PG8_SB(0, 1), cB + hstep, voffB); PG8_STAGE(PG8_SA(0, 0), cA, voffA); PG8_STAGE(PG8_SA(0, 1), cA + hstep, voffA);
;     if (wr == 1) PG8_BAR;
;     PG8_WAIT_V(2); PG8_BAR;
;     PG8_STAGE(PG8_SB(1, 0), cB + kstep, voffB); PG8_STAGE(PG8_SA(1, 0), cA + kstep, voffA); PG8_STAGE(PG8_SB(1, 1), cB + hstep + kstep, voffB);
;     PG8_WAIT_V(6); PG8_BAR;
.LBB0_382:
	v_bfe_u32 v20, v18, 4, 2
	s_lshl_b32 s10, s10, 5
	v_and_b32_e32 v19, 15, v18
	v_lshlrev_b32_e32 v21, 4, v20
	v_lshlrev_b32_e32 v18, 2, v18
	s_and_b32 s22, s10, 0x60
	v_lshl_or_b32 v1, s11, 6, v19
	v_lshl_or_b32 v19, v19, 6, v21
	s_lshl_b32 s11, s11, 13
	v_and_b32_e32 v18, 32, v18
	s_lshl_b32 s10, s22, 7
	s_add_i32 m0, s6, 0x18000
	v_lshl_add_u64 v[8:9], v[8:9], 0, s[34:35]
	v_bitop3_b32 v21, v19, s11, v18 bitop3:0xde
	v_bitop3_b32 v135, v19, s10, v18 bitop3:0xde
	s_waitcnt vmcnt(2)
	s_barrier
	global_load_lds_dwordx4 v[8:9], off
	v_lshl_add_u64 v[6:7], v[6:7], 0, s[34:35]
	s_add_i32 m0, s6, 0x1a000
	s_add_i32 s10, s6, 0x8000
	s_add_i32 s11, s6, 0xa000
	global_load_lds_dwordx4 v[6:7], off
	v_lshl_add_u64 v[2:3], v[2:3], 0, s[34:35]
	s_mov_b32 m0, s10
	s_add_u32 s16, s0, 0x160080
	global_load_lds_dwordx4 v[2:3], off
	v_lshl_add_u64 v[2:3], v[4:5], 0, s[34:35]
	s_mov_b32 m0, s11
	s_addc_u32 s17, s1, 0
	global_load_lds_dwordx4 v[2:3], off
	s_add_i32 m0, s6, 0x1c000
	v_lshl_add_u64 v[2:3], s[16:17], 0, v[132:133]
	global_load_lds_dwordx4 v[2:3], off
	v_lshl_add_u64 v[2:3], s[16:17], 0, v[130:131]
	s_add_i32 m0, s6, 0x1e000
	s_movk_i32 s23, 0x1600
	global_load_lds_dwordx4 v[2:3], off
	v_lshl_or_b32 v134, v20, 2, s22
	v_lshrrev_b32_e32 v3, 1, v15
	v_mul_lo_u32 v2, v14, s23
	s_mov_b32 s22, 0x16000
	v_mad_u64_u32 v[2:3], s[16:17], v3, s22, v[2:3]
	v_or_b32_e32 v2, v2, v16
	v_add_lshl_u32 v2, v2, v17, 1
	v_mov_b32_e32 v3, v0
	s_mov_b64 s[30:31], 0x160080
	v_lshl_add_u64 v[136:137], v[2:3], 0, s[30:31]
	v_lshrrev_b32_e32 v3, 1, v10
	v_mul_lo_u32 v2, v11, s23
	v_mad_u64_u32 v[2:3], s[16:17], v3, s22, v[2:3]
	s_waitcnt vmcnt(6)
	v_or_b32_e32 v2, v2, v12
	s_cmpk_lt_u32 s20, 0x100
	v_add_lshl_u32 v2, v2, v13, 1
	v_mov_b32_e32 v3, v0
	s_sext_i32_i8 s70, s21
	s_cselect_b64 s[20:21], -1, 0
	v_lshl_add_u64 v[138:139], v[2:3], 0, s[30:31]
	s_mov_b32 s22, 0
	v_add_u32_e32 v170, 0, v21
	s_barrier
	s_cmp_eq_u64 s[20:21], 0
	s_cbranch_scc1 .Lmy_pr_385
	s_setprio 1

;     __device__ bool next(int i, Unit& u) const { const int idx = i * G + c; if (idx >= 64) return false; u.kp = idx & 3; u.pn = (idx >> 2) & 7; u.pm = 192 + (idx >> 5); return true; }
; #define PG8_STAGE(bufoff, gbase, voff) do { _Pragma("unroll") for (int _i = 0; _i < 2; ++_i) \
;         __builtin_amdgcn_global_load_lds((const unsigned*)((const char*)(gbase) + (voff)[_i]), (LAS unsigned*)(lds + (bufoff) + ldsw + _i * 8192), 16, 0, 0); } while (0)
; #define PG8_WAIT_V(n) asm volatile("s_waitcnt vmcnt(" #n ")" ::: "memory")
; #define PG8_BAR __builtin_amdgcn_s_barrier()
; template <class Epi, class Sched = StaticOrder, bool ALIGN_EPI = true>
; __device__ __forceinline__ void gemm_phase(LAS unsigned char* lds, const Gemm g, const Sched& S, const Epi& E) {
;     ...
;     for (int i = 0; i < 2; ++i) { int R, C; stage_rc(tid * 16 + i * 8192, R, C); const int Rb = Epi::PERM ? ((R & ~31) + perm32(R & 31)) : R;
;         voffA[i] = (unsigned)(R * g.ld + C) * 2u; voffB[i] = (unsigned)(Rb * g.ld + C) * 2u; }
;     const size_t kstep = (size_t)(BK * 2);
;     const size_t hstep = (size_t)HALF * g.ld * 2;
;     const size_t tstep = 2 * hstep;
;     const unsigned ldsw = (unsigned)wid * 1024u;
;     const int aoff = lds_byte(wr * 64 + fr, fq * 8), boff = lds_byte(wc * 32 + fr, fq * 8);
;     ...
;     Unit cur, nxt; int ui = 0;
;     if (!S.next(0, cur)) return;
;     f32x4 acc[2][2][4][2];
; #pragma unroll
;     for (int a = 0; a < 2; ++a)
; #pragma unroll
;         for (int b = 0; b < 2; ++b)
; #pragma unroll
;             for (int m = 0; m < 4; ++m)
; #pragma unroll
;                 for (int n = 0; n < 2; ++n) acc[a][b][m][n] = (f32x4){0.f, 0.f, 0.f, 0.f};
;     bf16x8 At[4][2], B0[2][2], B1[2][2];
;     const char* cA = (const char*)g.A + (size_t)cur.pm * tstep + (size_t)cur.kp * K * 2; const char* cB = (const char*)g.Bt + (size_t)cur.pn * tstep + (size_t)cur.kp * K * 2;
;     PG8_STAGE(PG8_SB(0, 0), cB, voffB); PG8_STAGE(PG8_SB(0, 1), cB + hstep, voffB); PG8_STAGE(PG8_SA(0, 0), cA, voffA); PG8_STAGE(PG8_SA(0, 1), cA + hstep, voffA);
;     if (wr == 1) PG8_BAR;
;     PG8_WAIT_V(2); PG8_BAR;
;     PG8_STAGE(PG8_SB(1, 0), cB + kstep, voffB); PG8_STAGE(PG8_SA(1, 0), cA + kstep, voffA); PG8_STAGE(PG8_SB(1, 1), cB + hstep + kstep, voffB);
;     PG8_WAIT_V(6); PG8_BAR;
.LBB0_461:
	v_lshrrev_b32_e32 v18, 1, v16
	v_and_b32_e32 v18, 24, v18
	s_lshl_b32 s7, s7, 5
	v_and_b32_e32 v17, 15, v16
	v_lshlrev_b32_e32 v19, 1, v18
	v_lshlrev_b32_e32 v16, 2, v16
	s_and_b32 s16, s7, 0x60
	v_lshl_or_b32 v1, s8, 6, v17
	v_lshl_or_b32 v17, v17, 6, v19
	s_lshl_b32 s8, s8, 13
	v_and_b32_e32 v16, 32, v16
	s_lshl_b32 s7, s16, 7
	s_add_i32 m0, s23, 0x18000
	v_lshl_add_u64 v[8:9], v[8:9], 0, s[34:35]
	v_bitop3_b32 v19, v17, s8, v16 bitop3:0xde
	v_bitop3_b32 v144, v17, s7, v16 bitop3:0xde
	s_waitcnt vmcnt(2)
	s_barrier
	global_load_lds_dwordx4 v[8:9], off
	v_lshl_add_u64 v[6:7], v[6:7], 0, s[34:35]
	s_add_i32 m0, s23, 0x1a000
	s_add_i32 s7, s23, 0x8000
	s_add_i32 s8, s23, 0xa000
	global_load_lds_dwordx4 v[6:7], off
	v_lshl_add_u64 v[2:3], v[2:3], 0, s[34:35]
	s_mov_b32 m0, s7
	s_add_u32 s10, s46, 0x80080
	global_load_lds_dwordx4 v[2:3], off
	v_lshl_add_u64 v[2:3], v[4:5], 0, s[34:35]
	s_mov_b32 m0, s8
	s_addc_u32 s11, s47, 0
	global_load_lds_dwordx4 v[2:3], off
	s_add_i32 m0, s23, 0x1c000
	v_lshl_add_u64 v[2:3], s[10:11], 0, v[134:135]
	global_load_lds_dwordx4 v[2:3], off
	v_lshl_add_u64 v[2:3], s[10:11], 0, v[130:131]
	s_add_i32 m0, s23, 0x1e000
	s_cmpk_lt_u32 s9, 0x100
	global_load_lds_dwordx4 v[2:3], off
	v_lshlrev_b32_e32 v2, 15, v14
	v_and_b32_e32 v2, 0xffff0000, v2
	v_lshl_add_u32 v2, v13, 12, v2
	v_and_b32_e32 v3, 1, v14
	v_lshl_or_b32 v2, v3, 6, v2
	v_lshl_add_u32 v138, v15, 1, v2
	v_lshlrev_b32_e32 v2, 15, v10
	v_and_b32_e32 v2, 0xffff0000, v2
	s_waitcnt vmcnt(6)
	v_lshl_add_u32 v2, v11, 12, v2
	v_and_b32_e32 v3, 1, v10
	v_lshl_or_b32 v2, v3, 6, v2
	s_sext_i32_i16 s1, s12
	s_cselect_b64 s[12:13], -1, 0
	v_or_b32_e32 v145, s16, v18
	v_mov_b32_e32 v139, v0
	v_lshl_add_u32 v140, v12, 1, v2
	v_mov_b32_e32 v141, v0
	s_mov_b32 s9, 0
	v_add_u32_e32 v146, 0, v19
	s_barrier
	s_waitcnt vmcnt(0)
	s_cmp_eq_u64 s[12:13], 0
	s_cbranch_scc1 .Lmy_pr_464
	s_setprio 1
